# layer-3 decode attention: the same restructure (Q fragments in registers, convert/MFMA overlap, path-specific vmcnt, PV reads 6 ahead) applied to the first decode loop copy as well
# speedup vs baseline: 1.0067x; 1.0067x over previous
.LBB0_3630:
	s_lshl_b32 s1, s2, 14
	s_ashr_i32 s11, s10, 31
	s_add_i32 s13, s1, 0
	s_lshl_b64 s[8:9], s[10:11], 3
	s_ashr_i32 s14, s2, 31
	s_add_u32 s1, s8, s2
	s_addc_u32 s8, s9, s14
	s_mul_i32 s8, s8, 0x28000
	s_mul_hi_u32 s9, s1, 0x28000
	s_add_i32 s9, s9, s8
	s_mul_i32 s1, s1, 0x28000
	s_add_u32 s8, s69, s1
	s_addc_u32 s9, s72, s9
	v_lshlrev_b32_e32 v0, 3, v6
	s_waitcnt lgkmcnt(0)
	s_barrier
	global_load_dwordx2 v[74:75], v0, s[8:9]
	global_load_dwordx2 v[76:77], v0, s[8:9] offset:512
	global_load_dwordx2 v[78:79], v0, s[8:9] offset:1024
	global_load_dwordx2 v[80:81], v0, s[8:9] offset:1536
	global_load_dwordx2 v[82:83], v0, s[8:9] offset:2048
	global_load_dwordx2 v[84:85], v0, s[8:9] offset:2560
	global_load_dwordx2 v[86:87], v0, s[8:9] offset:3072
	global_load_dwordx2 v[88:89], v0, s[8:9] offset:3584
	v_lshl_add_u64 v[2:3], s[8:9], 0, v[0:1]
	v_add_co_u32_e32 v2, vcc, s94, v2
	v_lshrrev_b32_e32 v8, 4, v6
	s_nop 0
	v_addc_co_u32_e32 v3, vcc, 0, v3, vcc
	global_load_dwordx2 v[90:91], v[2:3], off
	global_load_dwordx2 v[92:93], v[2:3], off offset:512
	v_lshlrev_b32_e32 v2, 1, v7
	v_and_b32_e32 v3, 14, v2
	v_bitop3_b32 v2, v2, v8, 14 bitop3:0x6c
	v_lshrrev_b32_e32 v9, 2, v7
	v_lshl_add_u32 v10, v7, 9, s13
	v_lshlrev_b32_e32 v7, 4, v2
	v_bitop3_b32 v2, v8, v3, 4 bitop3:0x36
	v_lshlrev_b32_e32 v11, 4, v2
	v_bitop3_b32 v2, v8, v3, 8 bitop3:0x36
	v_lshlrev_b32_e32 v12, 4, v2
	v_bitop3_b32 v2, v8, v3, 12 bitop3:0x36
	v_lshlrev_b32_e32 v13, 4, v2
	v_bitop3_b32 v2, v8, v3, 16 bitop3:0x36
	v_lshlrev_b32_e32 v14, 4, v2
	v_bitop3_b32 v2, v8, v3, 20 bitop3:0x36
	v_lshlrev_b32_e32 v15, 4, v2
	v_bitop3_b32 v2, v8, v3, 24 bitop3:0x36
	v_lshlrev_b32_e32 v16, 4, v2
	v_bitop3_b32 v2, v8, v3, 28 bitop3:0x36
	v_lshlrev_b32_e32 v17, 4, v2
	v_lshlrev_b32_e32 v2, 2, v6
	v_xor_b32_e32 v114, 64, v2
	v_xor_b32_e32 v97, 0x80, v2
	v_lshl_or_b32 v2, v8, 2, v9
	s_add_u32 s2, s4, s2
	v_lshlrev_b32_e32 v6, 1, v2
	s_addc_u32 s8, s5, s14
	v_bfe_u32 v3, v5, 1, 1
	v_and_b32_e32 v8, 14, v6
	s_mul_i32 s8, s8, 0x28000
	s_mul_hi_u32 s9, s2, 0x28000
	v_or_b32_e32 v8, v8, v3
	v_or_b32_e32 v9, 2, v3
	v_or_b32_e32 v18, 4, v3
	v_or_b32_e32 v19, 6, v3
	v_or_b32_e32 v20, 8, v3
	v_or_b32_e32 v21, 10, v3
	v_or_b32_e32 v22, 12, v3
	v_bitop3_b32 v23, v6, v3, 14 bitop3:0x4e
	v_or_b32_e32 v24, v6, v3
	v_or_b32_e32 v25, 18, v3
	v_or_b32_e32 v26, 20, v3
	v_or_b32_e32 v27, 22, v3
	v_or_b32_e32 v28, 24, v3
	v_or_b32_e32 v29, 26, v3
	v_or_b32_e32 v30, 28, v3
	v_or_b32_e32 v3, 30, v3
	s_add_i32 s9, s9, s8
	s_mul_i32 s2, s2, 0x28000
	v_lshlrev_b32_e32 v5, 3, v5
	v_lshl_add_u32 v2, v2, 9, s13
	v_bitop3_b32 v9, v6, v9, 14 bitop3:0x6c
	v_bitop3_b32 v18, v6, v18, 14 bitop3:0x6c
	v_bitop3_b32 v19, v6, v19, 14 bitop3:0x6c
	v_bitop3_b32 v20, v6, v20, 14 bitop3:0x6c
	v_bitop3_b32 v21, v6, v21, 14 bitop3:0x6c
	v_bitop3_b32 v22, v6, v22, 14 bitop3:0x6c
	v_lshl_or_b32 v24, v24, 4, v151
	v_bitop3_b32 v25, v6, v25, 14 bitop3:0x6c
	v_bitop3_b32 v26, v6, v26, 14 bitop3:0x6c
	v_bitop3_b32 v27, v6, v27, 14 bitop3:0x6c
	v_bitop3_b32 v28, v6, v28, 14 bitop3:0x6c
	v_bitop3_b32 v29, v6, v29, 14 bitop3:0x6c
	v_bitop3_b32 v30, v6, v30, 14 bitop3:0x6c
	v_bitop3_b32 v3, v6, v3, 14 bitop3:0x6c
	s_add_u32 s8, s75, s2
	v_and_b32_e32 v5, 8, v5
	v_lshl_add_u32 v8, v8, 4, v2
	v_lshl_add_u32 v9, v9, 4, v2
	v_lshl_add_u32 v18, v18, 4, v2
	v_lshl_add_u32 v19, v19, 4, v2
	v_lshl_add_u32 v20, v20, 4, v2
	v_lshl_add_u32 v21, v21, 4, v2
	v_lshl_add_u32 v22, v22, 4, v2
	v_lshl_add_u32 v23, v23, 4, v2
	v_add_u32_e32 v24, v2, v24
	v_lshl_add_u32 v25, v25, 4, v2
	v_lshl_add_u32 v26, v26, 4, v2
	v_lshl_add_u32 v27, v27, 4, v2
	v_lshl_add_u32 v28, v28, 4, v2
	v_lshl_add_u32 v29, v29, 4, v2
	v_lshl_add_u32 v30, v30, 4, v2
	v_lshl_add_u32 v6, v3, 4, v2
	s_addc_u32 s9, s76, s9
	v_mov_b32_e32 v2, v1
	v_mov_b32_e32 v3, v1
	v_lshl_add_u64 v[94:95], s[8:9], 0, v[0:1]
	v_mov_b32_e32 v0, v1
	v_add_u32_e32 v116, v8, v5
	v_add_u32_e32 v117, v9, v5
	v_add_u32_e32 v118, v18, v5
	v_add_u32_e32 v119, v19, v5
	v_add_u32_e32 v120, v20, v5
	v_add_u32_e32 v121, v21, v5
	v_add_u32_e32 v122, v22, v5
	v_add_u32_e32 v123, v23, v5
	v_add_u32_e32 v124, v24, v5
	v_add_u32_e32 v125, v25, v5
	v_add_u32_e32 v126, v26, v5
	v_add_u32_e32 v127, v27, v5
	v_add_u32_e32 v128, v28, v5
	v_add_u32_e32 v129, v29, v5
	v_add_u32_e32 v130, v30, v5
	v_add_u32_e32 v131, v6, v5
	v_add_u32_e32 v4, 0, v4
	v_add_u32_e32 v133, v10, v7
	v_add_u32_e32 v134, v10, v11
	v_add_u32_e32 v135, v10, v12
	v_add_u32_e32 v136, v10, v13
	v_add_u32_e32 v137, v10, v14
	v_add_u32_e32 v138, v10, v15
	v_add_u32_e32 v139, v10, v16
	v_add_u32_e32 v140, v10, v17
	v_mov_b64_e32 v[64:65], v[2:3]
	v_mov_b64_e32 v[60:61], v[2:3]
	v_mov_b64_e32 v[56:57], v[2:3]
	v_mov_b64_e32 v[52:53], v[2:3]
	v_mov_b64_e32 v[48:49], v[2:3]
	v_mov_b64_e32 v[44:45], v[2:3]
	v_mov_b64_e32 v[40:41], v[2:3]
	v_mov_b64_e32 v[36:37], v[2:3]
	v_mov_b64_e32 v[32:33], v[2:3]
	v_mov_b64_e32 v[28:29], v[2:3]
	v_mov_b64_e32 v[24:25], v[2:3]
	v_mov_b64_e32 v[20:21], v[2:3]
	v_mov_b64_e32 v[16:17], v[2:3]
	v_mov_b64_e32 v[12:13], v[2:3]
	v_mov_b64_e32 v[8:9], v[2:3]
	v_add_u32_e32 v132, 0x21000, v4
	v_mov_b64_e32 v[62:63], v[0:1]
	v_mov_b64_e32 v[58:59], v[0:1]
	v_mov_b64_e32 v[54:55], v[0:1]
	v_mov_b64_e32 v[50:51], v[0:1]
	v_mov_b64_e32 v[46:47], v[0:1]
	v_mov_b64_e32 v[42:43], v[0:1]
	v_mov_b64_e32 v[38:39], v[0:1]
	v_mov_b64_e32 v[34:35], v[0:1]
	v_mov_b64_e32 v[30:31], v[0:1]
	v_mov_b64_e32 v[26:27], v[0:1]
	v_mov_b64_e32 v[22:23], v[0:1]
	v_mov_b64_e32 v[18:19], v[0:1]
	v_mov_b64_e32 v[14:15], v[0:1]
	v_mov_b64_e32 v[10:11], v[0:1]
	v_mov_b64_e32 v[6:7], v[0:1]
	v_mov_b64_e32 v[4:5], v[2:3]
	s_mov_b32 s1, 0
	v_mov_b32_e32 v115, 0
	v_mov_b32_e32 v96, 0xf149f2ca
	v_mov_b64_e32 v[2:3], v[0:1]
	ds_read_b128 v[160:163], v132
	ds_read_b128 v[164:167], v132 offset:1024
	ds_read_b128 v[168:171], v132 offset:2048
	ds_read_b128 v[172:175], v132 offset:3072
	ds_read_b128 v[176:179], v132 offset:4096
	ds_read_b128 v[180:183], v132 offset:5120
	ds_read_b128 v[184:187], v132 offset:6144
	ds_read_b128 v[188:191], v132 offset:7168
	ds_read_b128 v[192:195], v132 offset:8192
	ds_read_b128 v[196:199], v132 offset:9216
	s_waitcnt lgkmcnt(0)
	s_branch .LBB0_3632
.LBB0_3631:
	ds_read_b64_tr_b16 v[224:225], v116
	ds_read_b64_tr_b16 v[226:227], v116 offset:8192
	ds_read_b64_tr_b16 v[228:229], v117
	ds_read_b64_tr_b16 v[230:231], v117 offset:8192
	ds_read_b64_tr_b16 v[232:233], v118
	ds_read_b64_tr_b16 v[234:235], v118 offset:8192
	ds_read_b64_tr_b16 v[236:237], v119
	ds_read_b64_tr_b16 v[238:239], v119 offset:8192
	ds_read_b64_tr_b16 v[240:241], v120
	ds_read_b64_tr_b16 v[242:243], v120 offset:8192
	ds_read_b64_tr_b16 v[244:245], v121
	ds_read_b64_tr_b16 v[246:247], v121 offset:8192
	v_sub_f32_e32 v0, v66, v96
	v_exp_f32_e32 v102, v0
	v_sub_f32_e32 v0, v70, v96
	v_exp_f32_e32 v103, v0
	v_sub_f32_e32 v0, v67, v96
	v_exp_f32_e32 v104, v0
	v_sub_f32_e32 v0, v71, v96
	v_exp_f32_e32 v105, v0
	v_sub_f32_e32 v0, v68, v96
	v_exp_f32_e32 v106, v0
	v_sub_f32_e32 v0, v72, v96
	v_exp_f32_e32 v107, v0
	v_sub_f32_e32 v0, v69, v96
	v_exp_f32_e32 v108, v0
	v_sub_f32_e32 v0, v73, v96
	v_exp_f32_e32 v109, v0
	v_cvt_pk_bf16_f32 v66, v102, v104
	v_cvt_pk_bf16_f32 v67, v106, v108
	v_cvt_pk_bf16_f32 v68, v103, v105
	v_cvt_pk_bf16_f32 v69, v107, v109
	v_pk_add_f32 v[102:103], v[102:103], v[104:105]
	v_pk_add_f32 v[104:105], v[106:107], v[108:109]
	v_add_f32_e64 v70, v102, v104
	v_add_f32_e64 v71, v103, v105
	v_add_f32_e32 v0, v70, v71
	v_add_f32_e32 v115, v115, v0
	s_waitcnt lgkmcnt(10)
	v_mfma_f32_16x16x32_bf16 v[62:65], v[224:227], v[66:69], v[62:65]
	ds_read_b64_tr_b16 v[224:225], v122
	ds_read_b64_tr_b16 v[226:227], v122 offset:8192
	s_waitcnt lgkmcnt(10)
	v_mfma_f32_16x16x32_bf16 v[58:61], v[228:231], v[66:69], v[58:61]
	ds_read_b64_tr_b16 v[228:229], v123
	ds_read_b64_tr_b16 v[230:231], v123 offset:8192
	s_waitcnt lgkmcnt(10)
	v_mfma_f32_16x16x32_bf16 v[54:57], v[232:235], v[66:69], v[54:57]
	ds_read_b64_tr_b16 v[232:233], v124
	ds_read_b64_tr_b16 v[234:235], v124 offset:8192
	s_waitcnt lgkmcnt(10)
	v_mfma_f32_16x16x32_bf16 v[50:53], v[236:239], v[66:69], v[50:53]
	ds_read_b64_tr_b16 v[236:237], v125
	ds_read_b64_tr_b16 v[238:239], v125 offset:8192
	s_waitcnt lgkmcnt(10)
	v_mfma_f32_16x16x32_bf16 v[46:49], v[240:243], v[66:69], v[46:49]
	ds_read_b64_tr_b16 v[240:241], v126
	ds_read_b64_tr_b16 v[242:243], v126 offset:8192
	s_waitcnt lgkmcnt(10)
	v_mfma_f32_16x16x32_bf16 v[42:45], v[244:247], v[66:69], v[42:45]
	ds_read_b64_tr_b16 v[244:245], v127
	ds_read_b64_tr_b16 v[246:247], v127 offset:8192
	s_waitcnt lgkmcnt(10)
	v_mfma_f32_16x16x32_bf16 v[38:41], v[224:227], v[66:69], v[38:41]
	ds_read_b64_tr_b16 v[224:225], v128
	ds_read_b64_tr_b16 v[226:227], v128 offset:8192
	s_waitcnt lgkmcnt(10)
	v_mfma_f32_16x16x32_bf16 v[34:37], v[228:231], v[66:69], v[34:37]
	ds_read_b64_tr_b16 v[228:229], v129
	ds_read_b64_tr_b16 v[230:231], v129 offset:8192
	s_waitcnt lgkmcnt(10)
	v_mfma_f32_16x16x32_bf16 v[30:33], v[232:235], v[66:69], v[30:33]
	ds_read_b64_tr_b16 v[232:233], v130
	ds_read_b64_tr_b16 v[234:235], v130 offset:8192
	s_waitcnt lgkmcnt(10)
	v_mfma_f32_16x16x32_bf16 v[26:29], v[236:239], v[66:69], v[26:29]
	ds_read_b64_tr_b16 v[236:237], v131
	ds_read_b64_tr_b16 v[238:239], v131 offset:8192
	s_waitcnt lgkmcnt(10)
	v_mfma_f32_16x16x32_bf16 v[22:25], v[240:243], v[66:69], v[22:25]
	s_waitcnt lgkmcnt(8)
	v_mfma_f32_16x16x32_bf16 v[18:21], v[244:247], v[66:69], v[18:21]
	s_waitcnt lgkmcnt(6)
	v_mfma_f32_16x16x32_bf16 v[14:17], v[224:227], v[66:69], v[14:17]
	s_waitcnt lgkmcnt(4)
	v_mfma_f32_16x16x32_bf16 v[10:13], v[228:231], v[66:69], v[10:13]
	s_waitcnt lgkmcnt(2)
	v_mfma_f32_16x16x32_bf16 v[6:9], v[232:235], v[66:69], v[6:9]
	s_waitcnt lgkmcnt(0)
	v_mfma_f32_16x16x32_bf16 v[2:5], v[236:239], v[66:69], v[2:5]
	s_mov_b64 s[14:15], 0x2800
	s_add_i32 s1, s1, 2
	v_lshl_add_u64 v[94:95], v[94:95], 0, s[14:15]
	s_and_b64 vcc, exec, s[8:9]
	s_cbranch_vccnz .LBB0_3636
.LBB0_3632:
	global_load_dwordx2 v[108:109], v[94:95], off offset:1024
	global_load_dwordx2 v[106:107], v[94:95], off offset:1536
	global_load_dwordx2 v[104:105], v[94:95], off offset:2048
	global_load_dwordx2 v[102:103], v[94:95], off offset:2560
	global_load_dwordx2 v[100:101], v[94:95], off offset:3072
	global_load_dwordx2 v[98:99], v[94:95], off offset:3584
	v_add_co_u32_e32 v66, vcc, s94, v94
	s_nop 1
	v_addc_co_u32_e32 v67, vcc, 0, v95, vcc
	global_load_dwordx2 v[112:113], v[94:95], off
	global_load_dwordx2 v[110:111], v[94:95], off offset:512
	global_load_dwordx2 v[72:73], v[66:67], off
	global_load_dwordx2 v[70:71], v[66:67], off offset:512
	s_waitcnt vmcnt(19)
	v_cvt_pk_f32_fp8_e32 v[208:209], v74
	v_cvt_pk_f32_fp8_sdwa v[210:211], v74 src0_sel:WORD_1
	v_cvt_pk_f32_fp8_e32 v[212:213], v75
	v_cvt_pk_f32_fp8_sdwa v[214:215], v75 src0_sel:WORD_1
	v_cvt_pk_bf16_f32 v200, v208, v209
	v_cvt_pk_bf16_f32 v201, v210, v211
	v_cvt_pk_bf16_f32 v202, v212, v213
	v_cvt_pk_bf16_f32 v203, v214, v215
	s_waitcnt vmcnt(18)
	v_cvt_pk_f32_fp8_e32 v[208:209], v76
	v_cvt_pk_f32_fp8_sdwa v[210:211], v76 src0_sel:WORD_1
	v_cvt_pk_f32_fp8_e32 v[212:213], v77
	v_cvt_pk_f32_fp8_sdwa v[214:215], v77 src0_sel:WORD_1
	v_cvt_pk_bf16_f32 v204, v208, v209
	v_cvt_pk_bf16_f32 v205, v210, v211
	v_cvt_pk_bf16_f32 v206, v212, v213
	v_cvt_pk_bf16_f32 v207, v214, v215
	v_mfma_f32_16x16x32_bf16 v[216:219], v[200:203], v[160:163], 0
	ds_write_b128 v133, v[200:203]
	s_waitcnt vmcnt(17)
	v_cvt_pk_f32_fp8_e32 v[208:209], v78
	v_cvt_pk_f32_fp8_sdwa v[210:211], v78 src0_sel:WORD_1
	v_cvt_pk_f32_fp8_e32 v[212:213], v79
	v_cvt_pk_f32_fp8_sdwa v[214:215], v79 src0_sel:WORD_1
	v_cvt_pk_bf16_f32 v200, v208, v209
	v_cvt_pk_bf16_f32 v201, v210, v211
	v_cvt_pk_bf16_f32 v202, v212, v213
	v_cvt_pk_bf16_f32 v203, v214, v215
	v_mfma_f32_16x16x32_bf16 v[216:219], v[204:207], v[164:167], v[216:219]
	ds_write_b128 v134, v[204:207]
	s_waitcnt vmcnt(16)
	v_cvt_pk_f32_fp8_e32 v[208:209], v80
	v_cvt_pk_f32_fp8_sdwa v[210:211], v80 src0_sel:WORD_1
	v_cvt_pk_f32_fp8_e32 v[212:213], v81
	v_cvt_pk_f32_fp8_sdwa v[214:215], v81 src0_sel:WORD_1
	v_cvt_pk_bf16_f32 v204, v208, v209
	v_cvt_pk_bf16_f32 v205, v210, v211
	v_cvt_pk_bf16_f32 v206, v212, v213
	v_cvt_pk_bf16_f32 v207, v214, v215
	v_mfma_f32_16x16x32_bf16 v[216:219], v[200:203], v[168:171], v[216:219]
	ds_write_b128 v135, v[200:203]
	s_waitcnt vmcnt(15)
	v_cvt_pk_f32_fp8_e32 v[208:209], v82
	v_cvt_pk_f32_fp8_sdwa v[210:211], v82 src0_sel:WORD_1
	v_cvt_pk_f32_fp8_e32 v[212:213], v83
	v_cvt_pk_f32_fp8_sdwa v[214:215], v83 src0_sel:WORD_1
	v_cvt_pk_bf16_f32 v200, v208, v209
	v_cvt_pk_bf16_f32 v201, v210, v211
	v_cvt_pk_bf16_f32 v202, v212, v213
	v_cvt_pk_bf16_f32 v203, v214, v215
	v_mfma_f32_16x16x32_bf16 v[216:219], v[204:207], v[172:175], v[216:219]
	ds_write_b128 v136, v[204:207]
	s_waitcnt vmcnt(14)
	v_cvt_pk_f32_fp8_e32 v[208:209], v84
	v_cvt_pk_f32_fp8_sdwa v[210:211], v84 src0_sel:WORD_1
	v_cvt_pk_f32_fp8_e32 v[212:213], v85
	v_cvt_pk_f32_fp8_sdwa v[214:215], v85 src0_sel:WORD_1
	v_cvt_pk_bf16_f32 v204, v208, v209
	v_cvt_pk_bf16_f32 v205, v210, v211
	v_cvt_pk_bf16_f32 v206, v212, v213
	v_cvt_pk_bf16_f32 v207, v214, v215
	v_mfma_f32_16x16x32_bf16 v[216:219], v[200:203], v[176:179], v[216:219]
	ds_write_b128 v137, v[200:203]
	s_waitcnt vmcnt(13)
	v_cvt_pk_f32_fp8_e32 v[208:209], v86
	v_cvt_pk_f32_fp8_sdwa v[210:211], v86 src0_sel:WORD_1
	v_cvt_pk_f32_fp8_e32 v[212:213], v87
	v_cvt_pk_f32_fp8_sdwa v[214:215], v87 src0_sel:WORD_1
	v_cvt_pk_bf16_f32 v200, v208, v209
	v_cvt_pk_bf16_f32 v201, v210, v211
	v_cvt_pk_bf16_f32 v202, v212, v213
	v_cvt_pk_bf16_f32 v203, v214, v215
	v_mfma_f32_16x16x32_bf16 v[216:219], v[204:207], v[180:183], v[216:219]
	ds_write_b128 v138, v[204:207]
	s_waitcnt vmcnt(12)
	v_cvt_pk_f32_fp8_e32 v[208:209], v88
	v_cvt_pk_f32_fp8_sdwa v[210:211], v88 src0_sel:WORD_1
	v_cvt_pk_f32_fp8_e32 v[212:213], v89
	v_cvt_pk_f32_fp8_sdwa v[214:215], v89 src0_sel:WORD_1
	v_cvt_pk_bf16_f32 v204, v208, v209
	v_cvt_pk_bf16_f32 v205, v210, v211
	v_cvt_pk_bf16_f32 v206, v212, v213
	v_cvt_pk_bf16_f32 v207, v214, v215
	v_mfma_f32_16x16x32_bf16 v[216:219], v[200:203], v[184:187], v[216:219]
	ds_write_b128 v139, v[200:203]
	s_waitcnt vmcnt(11)
	v_cvt_pk_f32_fp8_e32 v[208:209], v90
	v_cvt_pk_f32_fp8_sdwa v[210:211], v90 src0_sel:WORD_1
	v_cvt_pk_f32_fp8_e32 v[212:213], v91
	v_cvt_pk_f32_fp8_sdwa v[214:215], v91 src0_sel:WORD_1
	v_cvt_pk_bf16_f32 v200, v208, v209
	v_cvt_pk_bf16_f32 v201, v210, v211
	v_cvt_pk_bf16_f32 v202, v212, v213
	v_cvt_pk_bf16_f32 v203, v214, v215
	v_mfma_f32_16x16x32_bf16 v[216:219], v[204:207], v[188:191], v[216:219]
	ds_write_b128 v140, v[204:207]
	s_waitcnt vmcnt(10)
	v_cvt_pk_f32_fp8_e32 v[208:209], v92
	v_cvt_pk_f32_fp8_sdwa v[210:211], v92 src0_sel:WORD_1
	v_cvt_pk_f32_fp8_e32 v[212:213], v93
	v_cvt_pk_f32_fp8_sdwa v[214:215], v93 src0_sel:WORD_1
	v_cvt_pk_bf16_f32 v204, v208, v209
	v_cvt_pk_bf16_f32 v205, v210, v211
	v_cvt_pk_bf16_f32 v206, v212, v213
	v_cvt_pk_bf16_f32 v207, v214, v215
	v_mfma_f32_16x16x32_bf16 v[216:219], v[200:203], v[192:195], v[216:219]
	s_nop 1
	v_mfma_f32_16x16x32_bf16 v[66:69], v[204:207], v[196:199], v[216:219]
	s_cmp_gt_u32 s1, 29
	s_cselect_b64 s[8:9], -1, 0
	s_and_b64 vcc, exec, s[8:9]
	s_cbranch_vccnz .LBB0_3634
	v_add_co_u32_e32 v84, vcc, 0x1000, v94
	s_nop 1
	v_addc_co_u32_e32 v85, vcc, 0, v95, vcc
	v_add_co_u32_e32 v92, vcc, 0x2000, v94
	global_load_dwordx2 v[74:75], v[84:85], off offset:1024
	global_load_dwordx2 v[76:77], v[84:85], off offset:1536
	global_load_dwordx2 v[78:79], v[84:85], off offset:2048
	global_load_dwordx2 v[80:81], v[84:85], off offset:2560
	v_addc_co_u32_e32 v93, vcc, 0, v95, vcc
	global_load_dwordx2 v[82:83], v[84:85], off offset:3072
	s_nop 0
	global_load_dwordx2 v[84:85], v[84:85], off offset:3584
	s_nop 0
	global_load_dwordx2 v[86:87], v[92:93], off
	global_load_dwordx2 v[88:89], v[92:93], off offset:512
	global_load_dwordx2 v[90:91], v[92:93], off offset:1024
	s_nop 0
	global_load_dwordx2 v[92:93], v[92:93], off offset:1536
	s_waitcnt vmcnt(13)
	v_cvt_pk_f32_fp8_e32 v[208:209], v112
	v_cvt_pk_f32_fp8_sdwa v[210:211], v112 src0_sel:WORD_1
	v_cvt_pk_f32_fp8_e32 v[212:213], v113
	v_cvt_pk_f32_fp8_sdwa v[214:215], v113 src0_sel:WORD_1
	v_cvt_pk_bf16_f32 v200, v208, v209
	v_cvt_pk_bf16_f32 v201, v210, v211
	v_cvt_pk_bf16_f32 v202, v212, v213
	v_cvt_pk_bf16_f32 v203, v214, v215
	s_waitcnt vmcnt(12)
	v_cvt_pk_f32_fp8_e32 v[208:209], v110
	v_cvt_pk_f32_fp8_sdwa v[210:211], v110 src0_sel:WORD_1
	v_cvt_pk_f32_fp8_e32 v[212:213], v111
	v_cvt_pk_f32_fp8_sdwa v[214:215], v111 src0_sel:WORD_1
	v_cvt_pk_bf16_f32 v204, v208, v209
	v_cvt_pk_bf16_f32 v205, v210, v211
	v_cvt_pk_bf16_f32 v206, v212, v213
	v_cvt_pk_bf16_f32 v207, v214, v215
	v_mfma_f32_16x16x32_bf16 v[220:223], v[200:203], v[160:163], 0
	ds_write_b128 v133, v[200:203] offset:8192
	v_cvt_pk_f32_fp8_e32 v[208:209], v108
	v_cvt_pk_f32_fp8_sdwa v[210:211], v108 src0_sel:WORD_1
	v_cvt_pk_f32_fp8_e32 v[212:213], v109
	v_cvt_pk_f32_fp8_sdwa v[214:215], v109 src0_sel:WORD_1
	v_cvt_pk_bf16_f32 v200, v208, v209
	v_cvt_pk_bf16_f32 v201, v210, v211
	v_cvt_pk_bf16_f32 v202, v212, v213
	v_cvt_pk_bf16_f32 v203, v214, v215
	v_mfma_f32_16x16x32_bf16 v[220:223], v[204:207], v[164:167], v[220:223]
	ds_write_b128 v134, v[204:207] offset:8192
	v_cvt_pk_f32_fp8_e32 v[208:209], v106
	v_cvt_pk_f32_fp8_sdwa v[210:211], v106 src0_sel:WORD_1
	v_cvt_pk_f32_fp8_e32 v[212:213], v107
	v_cvt_pk_f32_fp8_sdwa v[214:215], v107 src0_sel:WORD_1
	v_cvt_pk_bf16_f32 v204, v208, v209
	v_cvt_pk_bf16_f32 v205, v210, v211
	v_cvt_pk_bf16_f32 v206, v212, v213
	v_cvt_pk_bf16_f32 v207, v214, v215
	v_mfma_f32_16x16x32_bf16 v[220:223], v[200:203], v[168:171], v[220:223]
	ds_write_b128 v135, v[200:203] offset:8192
	v_cvt_pk_f32_fp8_e32 v[208:209], v104
	v_cvt_pk_f32_fp8_sdwa v[210:211], v104 src0_sel:WORD_1
	v_cvt_pk_f32_fp8_e32 v[212:213], v105
	v_cvt_pk_f32_fp8_sdwa v[214:215], v105 src0_sel:WORD_1
	v_cvt_pk_bf16_f32 v200, v208, v209
	v_cvt_pk_bf16_f32 v201, v210, v211
	v_cvt_pk_bf16_f32 v202, v212, v213
	v_cvt_pk_bf16_f32 v203, v214, v215
	v_mfma_f32_16x16x32_bf16 v[220:223], v[204:207], v[172:175], v[220:223]
	ds_write_b128 v136, v[204:207] offset:8192
	v_cvt_pk_f32_fp8_e32 v[208:209], v102
	v_cvt_pk_f32_fp8_sdwa v[210:211], v102 src0_sel:WORD_1
	v_cvt_pk_f32_fp8_e32 v[212:213], v103
	v_cvt_pk_f32_fp8_sdwa v[214:215], v103 src0_sel:WORD_1
	v_cvt_pk_bf16_f32 v204, v208, v209
	v_cvt_pk_bf16_f32 v205, v210, v211
	v_cvt_pk_bf16_f32 v206, v212, v213
	v_cvt_pk_bf16_f32 v207, v214, v215
	v_mfma_f32_16x16x32_bf16 v[220:223], v[200:203], v[176:179], v[220:223]
	ds_write_b128 v137, v[200:203] offset:8192
	v_cvt_pk_f32_fp8_e32 v[208:209], v100
	v_cvt_pk_f32_fp8_sdwa v[210:211], v100 src0_sel:WORD_1
	v_cvt_pk_f32_fp8_e32 v[212:213], v101
	v_cvt_pk_f32_fp8_sdwa v[214:215], v101 src0_sel:WORD_1
	v_cvt_pk_bf16_f32 v200, v208, v209
	v_cvt_pk_bf16_f32 v201, v210, v211
	v_cvt_pk_bf16_f32 v202, v212, v213
	v_cvt_pk_bf16_f32 v203, v214, v215
	v_mfma_f32_16x16x32_bf16 v[220:223], v[204:207], v[180:183], v[220:223]
	ds_write_b128 v138, v[204:207] offset:8192
	v_cvt_pk_f32_fp8_e32 v[208:209], v98
	v_cvt_pk_f32_fp8_sdwa v[210:211], v98 src0_sel:WORD_1
	v_cvt_pk_f32_fp8_e32 v[212:213], v99
	v_cvt_pk_f32_fp8_sdwa v[214:215], v99 src0_sel:WORD_1
	v_cvt_pk_bf16_f32 v204, v208, v209
	v_cvt_pk_bf16_f32 v205, v210, v211
	v_cvt_pk_bf16_f32 v206, v212, v213
	v_cvt_pk_bf16_f32 v207, v214, v215
	v_mfma_f32_16x16x32_bf16 v[220:223], v[200:203], v[184:187], v[220:223]
	ds_write_b128 v139, v[200:203] offset:8192
	s_waitcnt vmcnt(11)
	v_cvt_pk_f32_fp8_e32 v[208:209], v72
	v_cvt_pk_f32_fp8_sdwa v[210:211], v72 src0_sel:WORD_1
	v_cvt_pk_f32_fp8_e32 v[212:213], v73
	v_cvt_pk_f32_fp8_sdwa v[214:215], v73 src0_sel:WORD_1
	v_cvt_pk_bf16_f32 v200, v208, v209
	v_cvt_pk_bf16_f32 v201, v210, v211
	v_cvt_pk_bf16_f32 v202, v212, v213
	v_cvt_pk_bf16_f32 v203, v214, v215
	v_mfma_f32_16x16x32_bf16 v[220:223], v[204:207], v[188:191], v[220:223]
	ds_write_b128 v140, v[204:207] offset:8192
	s_waitcnt vmcnt(10)
	v_cvt_pk_f32_fp8_e32 v[208:209], v70
	v_cvt_pk_f32_fp8_sdwa v[210:211], v70 src0_sel:WORD_1
	v_cvt_pk_f32_fp8_e32 v[212:213], v71
	v_cvt_pk_f32_fp8_sdwa v[214:215], v71 src0_sel:WORD_1
	v_cvt_pk_bf16_f32 v204, v208, v209
	v_cvt_pk_bf16_f32 v205, v210, v211
	v_cvt_pk_bf16_f32 v206, v212, v213
	v_cvt_pk_bf16_f32 v207, v214, v215
	v_mfma_f32_16x16x32_bf16 v[220:223], v[200:203], v[192:195], v[220:223]
	s_nop 1
	v_mfma_f32_16x16x32_bf16 v[70:73], v[204:207], v[196:199], v[220:223]
	s_branch .Lmy_a3a_join

.Lmy_a3a_join:
	v_max_f32_e32 v0, v67, v67
	s_nop 1
	v_max_f32_e32 v98, v66, v66
	v_max_f32_e32 v0, v98, v0
	v_max_f32_e32 v98, v69, v69
	v_max_f32_e32 v99, v68, v68
	v_max_f32_e32 v98, v99, v98
	v_max_f32_e32 v99, v73, v73
	v_max_f32_e32 v100, v72, v72
	v_max_f32_e32 v99, v100, v99
	v_max3_f32 v99, v70, v71, v99
	v_max3_f32 v0, v0, v98, v99
	ds_bpermute_b32 v98, v114, v0
	s_waitcnt lgkmcnt(0)
	v_max_f32_e32 v98, v98, v98
	v_max_f32_e32 v0, v0, v98
	ds_bpermute_b32 v98, v97, v0
	s_waitcnt lgkmcnt(0)
	v_max_f32_e32 v98, v98, v98
	v_max_f32_e32 v0, v0, v98
	v_add_f32_e32 v98, 0x41000000, v96
	v_cmp_gt_f32_e32 vcc, v0, v98
	s_cbranch_vccz .LBB0_3631
	v_max_f32_e32 v0, v0, v0
	v_max_f32_e32 v98, v96, v96
	v_max_f32_e32 v98, v98, v0
	v_sub_f32_e32 v0, v96, v98
	v_exp_f32_e32 v0, v0
	v_mov_b32_e32 v96, v98
	v_pk_mul_f32 v[64:65], v[64:65], v[0:1] op_sel_hi:[1,0]
	v_pk_mul_f32 v[62:63], v[62:63], v[0:1] op_sel_hi:[1,0]
	v_pk_mul_f32 v[60:61], v[60:61], v[0:1] op_sel_hi:[1,0]
	v_pk_mul_f32 v[58:59], v[58:59], v[0:1] op_sel_hi:[1,0]
	v_pk_mul_f32 v[56:57], v[56:57], v[0:1] op_sel_hi:[1,0]
	v_pk_mul_f32 v[54:55], v[54:55], v[0:1] op_sel_hi:[1,0]
	v_pk_mul_f32 v[52:53], v[52:53], v[0:1] op_sel_hi:[1,0]
	v_pk_mul_f32 v[50:51], v[50:51], v[0:1] op_sel_hi:[1,0]
	v_pk_mul_f32 v[48:49], v[48:49], v[0:1] op_sel_hi:[1,0]
	v_pk_mul_f32 v[46:47], v[46:47], v[0:1] op_sel_hi:[1,0]
	v_pk_mul_f32 v[44:45], v[44:45], v[0:1] op_sel_hi:[1,0]
	v_pk_mul_f32 v[42:43], v[42:43], v[0:1] op_sel_hi:[1,0]
	v_pk_mul_f32 v[40:41], v[40:41], v[0:1] op_sel_hi:[1,0]
	v_pk_mul_f32 v[38:39], v[38:39], v[0:1] op_sel_hi:[1,0]
	v_pk_mul_f32 v[36:37], v[36:37], v[0:1] op_sel_hi:[1,0]
	v_pk_mul_f32 v[34:35], v[34:35], v[0:1] op_sel_hi:[1,0]
	v_pk_mul_f32 v[32:33], v[32:33], v[0:1] op_sel_hi:[1,0]
	v_pk_mul_f32 v[30:31], v[30:31], v[0:1] op_sel_hi:[1,0]
	v_pk_mul_f32 v[28:29], v[28:29], v[0:1] op_sel_hi:[1,0]
	v_pk_mul_f32 v[26:27], v[26:27], v[0:1] op_sel_hi:[1,0]
	v_pk_mul_f32 v[24:25], v[24:25], v[0:1] op_sel_hi:[1,0]
	v_pk_mul_f32 v[22:23], v[22:23], v[0:1] op_sel_hi:[1,0]
	v_pk_mul_f32 v[20:21], v[20:21], v[0:1] op_sel_hi:[1,0]
	v_pk_mul_f32 v[18:19], v[18:19], v[0:1] op_sel_hi:[1,0]
	v_pk_mul_f32 v[16:17], v[16:17], v[0:1] op_sel_hi:[1,0]
	v_pk_mul_f32 v[14:15], v[14:15], v[0:1] op_sel_hi:[1,0]
	v_pk_mul_f32 v[12:13], v[12:13], v[0:1] op_sel_hi:[1,0]
	v_pk_mul_f32 v[10:11], v[10:11], v[0:1] op_sel_hi:[1,0]
	v_pk_mul_f32 v[8:9], v[8:9], v[0:1] op_sel_hi:[1,0]
	v_pk_mul_f32 v[6:7], v[6:7], v[0:1] op_sel_hi:[1,0]
	v_pk_mul_f32 v[4:5], v[4:5], v[0:1] op_sel_hi:[1,0]
	v_pk_mul_f32 v[2:3], v[2:3], v[0:1] op_sel_hi:[1,0]
	v_mul_f32_e32 v115, v115, v0
	s_branch .LBB0_3631
.LBB0_3636:
	v_mov_b32_e32 v66, v1
	ds_bpermute_b32 v0, v114, v115
	s_waitcnt lgkmcnt(0)
	v_add_f32_e32 v68, v115, v0
	v_mbcnt_lo_u32_b32 v66, -1, v66
	v_mbcnt_hi_u32_b32 v66, -1, v66
	v_add_u32_e32 v66, s33, v66
	ds_bpermute_b32 v69, v97, v68
	v_readfirstlane_b32 s13, v66
	s_ashr_i32 s1, s13, 6
	s_lshl_b32 s2, s1, 14
	v_and_b32_e32 v67, 63, v66
	s_add_i32 s2, s2, 0
	s_waitcnt lgkmcnt(0)
	v_lshl_add_u32 v0, v67, 2, s2
	ds_write2st64_b32 v0, v62, v63 offset1:1
	ds_write2st64_b32 v0, v64, v65 offset0:2 offset1:3
	ds_write2st64_b32 v0, v58, v59 offset0:4 offset1:5
	ds_write2st64_b32 v0, v60, v61 offset0:6 offset1:7
	ds_write2st64_b32 v0, v54, v55 offset0:8 offset1:9
	ds_write2st64_b32 v0, v56, v57 offset0:10 offset1:11
	ds_write2st64_b32 v0, v50, v51 offset0:12 offset1:13
	ds_write2st64_b32 v0, v52, v53 offset0:14 offset1:15
	ds_write2st64_b32 v0, v46, v47 offset0:16 offset1:17
	ds_write2st64_b32 v0, v48, v49 offset0:18 offset1:19
	ds_write2st64_b32 v0, v42, v43 offset0:20 offset1:21
	ds_write2st64_b32 v0, v44, v45 offset0:22 offset1:23
	ds_write2st64_b32 v0, v38, v39 offset0:24 offset1:25
	ds_write2st64_b32 v0, v40, v41 offset0:26 offset1:27
	ds_write2st64_b32 v0, v34, v35 offset0:28 offset1:29
	ds_write2st64_b32 v0, v36, v37 offset0:30 offset1:31
	ds_write2st64_b32 v0, v30, v31 offset0:32 offset1:33
	ds_write2st64_b32 v0, v32, v33 offset0:34 offset1:35
	ds_write2st64_b32 v0, v26, v27 offset0:36 offset1:37
	ds_write2st64_b32 v0, v28, v29 offset0:38 offset1:39
	ds_write2st64_b32 v0, v22, v23 offset0:40 offset1:41
	ds_write2st64_b32 v0, v24, v25 offset0:42 offset1:43
	ds_write2st64_b32 v0, v18, v19 offset0:44 offset1:45
	ds_write2st64_b32 v0, v20, v21 offset0:46 offset1:47
	ds_write2st64_b32 v0, v14, v15 offset0:48 offset1:49
	ds_write2st64_b32 v0, v16, v17 offset0:50 offset1:51
	ds_write2st64_b32 v0, v10, v11 offset0:52 offset1:53
	ds_write2st64_b32 v0, v12, v13 offset0:54 offset1:55
	ds_write2st64_b32 v0, v6, v7 offset0:56 offset1:57
	ds_write2st64_b32 v0, v8, v9 offset0:58 offset1:59
	ds_write2st64_b32 v0, v2, v3 offset0:60 offset1:61
	ds_write2st64_b32 v0, v4, v5 offset0:62 offset1:63
	v_and_b32_e32 v0, 15, v66
	v_cmp_gt_u32_e32 vcc, 16, v67
	v_cmp_lt_u32_e64 s[8:9], 15, v67
	v_lshlrev_b32_e32 v21, 3, v0
	s_and_saveexec_b64 s[14:15], s[8:9]
	s_xor_b64 s[8:9], exec, s[14:15]
	v_lshlrev_b32_e32 v2, 3, v0
	s_andn2_saveexec_b64 s[8:9], s[8:9]
	s_cbranch_execz .LBB0_3640
	s_lshl_b32 s2, s1, 7
	s_add_i32 s2, s2, 0
	v_add_u32_e32 v2, s2, v21
	s_waitcnt lgkmcnt(14)
	v_add_f32_e32 v97, v68, v69
	v_add_u32_e32 v2, 0x20000, v2
	ds_write_b64 v2, v[96:97]
	v_mov_b32_e32 v2, v21
